# speedup vs baseline: 1.0033x; 1.0033x over previous
;     __device__ __forceinline__ void operator()(AccRef acc, const pg8::Unit& u, int wr, int wc, int fr, int fq) const {
;         const int fb = 128 * u.pn + 32 * wc + 8 * fq;
;         const f32x4 zero = {0.f, 0.f, 0.f, 0.f};
;         f32x4 W0[2][2], W1[2][2], W2[2][2], BB[2][2];
; #pragma unroll
;         for (int n = 0; n < 2; ++n)
; #pragma unroll
;             for (int bj = 0; bj < 2; ++bj) { const int fc = bj * DFF + fb + 4 * n; W0[n][bj] = *(const f32x4*)(cw + fc); W1[n][bj] = *(const f32x4*)(cw + NUP + fc); W2[n][bj] = *(const f32x4*)(cw + 2 * NUP + fc); BB[n][bj] = *(const f32x4*)(cb + fc); }
; #pragma unroll
;         for (int n = 0; n < 2; ++n) {
;             const int fv = fb + 4 * n, fg = DFF + fb + 4 * n;
;             f32x4 w0[2], w1[2], w2[2], bb[2];
; #pragma unroll
;             for (int bj = 0; bj < 2; ++bj) { w0[bj] = W0[n][bj]; w1[bj] = W1[n][bj]; w2[bj] = W2[n][bj]; bb[bj] = BB[n][bj]; }
; #pragma unroll
;             for (int ai = 0; ai < 2; ++ai) {
;                 const int slab = u.pm * 4 + ai * 2 + wr;
;                 const bool bstart = (slab & 31) == 0, has_next = ((slab + 1) & 31) != 0;
;                 f32x4 cv[4], cg[4];
; #pragma unroll
;                 for (int bj = 0; bj < 2; ++bj) {
;                     const int fc = bj ? fg : fv;
;                     const f32x4 h0 = acc[ai][bj][0][n], h1 = acc[ai][bj][1][n], h2 = acc[ai][bj][2][n], h3 = acc[ai][bj][3][n];
;                     f32x4 s3 = dpp4<0x111>(h3), s2 = dpp4<0x111>(h2);
;                     if (fr == 0) { s3 = zero; s2 = zero; }
;                     const f32x4 c0 = bb[bj] + w0[bj] * s2 + w1[bj] * s3 + w2[bj] * h0;
;                     const f32x4 c1 = bb[bj] + w0[bj] * s3 + w1[bj] * h0 + w2[bj] * h1;
;                     const f32x4 c2 = bb[bj] + w0[bj] * h0 + w1[bj] * h1 + w2[bj] * h2;
;                     const f32x4 c3 = bb[bj] + w0[bj] * h1 + w1[bj] * h2 + w2[bj] * h3;
;                     if (bj == 0) { cv[0] = c0; cv[1] = c1; cv[2] = c2; cv[3] = c3; } else { cg[0] = c0; cg[1] = c1; cg[2] = c2; cg[3] = c3; }
;                     if (has_next && fr == 15) {
;                         const size_t o1 = ((size_t)(1 * NSLAB + slab + 1) * 2) * NUP;
;                         *(u32x2*)((bf16_t*)BND + o1 + fc) = pack4(w0[bj] * h2 + w1[bj] * h3); *(u32x2*)((bf16_t*)BND + o1 + NUP + fc) = pack4(w0[bj] * h3);
;                     }
;                 }
.LBB0_757:
	s_lshl_b32 s3, s4, 7
	v_mov_b32_e32 v246, v3
	v_mov_b32_e32 v68, v243
	s_or_b32 s3, s3, s58
	s_lshl_b32 s44, s2, 2
	v_lshl_add_u32 v218, v68, 3, s3
	v_ashrrev_i32_e32 v219, 31, v218
	v_add_u32_e32 v220, 0x1580, v218
	v_lshlrev_b64 v[80:81], 2, v[218:219]
	v_ashrrev_i32_e32 v221, 31, v220
	v_lshl_add_u64 v[68:69], s[14:15], 0, v[80:81]
	v_lshl_add_u64 v[72:73], s[18:19], 0, v[80:81]
	v_lshl_add_u64 v[82:83], s[20:21], 0, v[80:81]
	v_lshl_add_u64 v[84:85], s[16:17], 0, v[80:81]
	v_lshlrev_b64 v[96:97], 2, v[220:221]
	global_load_dwordx4 v[76:79], v[68:69], off offset:16
	global_load_dwordx4 v[168:171], v[68:69], off
	s_nop 0
	global_load_dwordx4 v[68:71], v[72:73], off offset:16
	global_load_dwordx4 v[172:175], v[72:73], off
	s_nop 0
	global_load_dwordx4 v[72:75], v[82:83], off offset:16
	global_load_dwordx4 v[164:167], v[82:83], off
	s_nop 0
	global_load_dwordx4 v[80:83], v[84:85], off offset:16
	global_load_dwordx4 v[176:179], v[84:85], off
	v_lshl_add_u64 v[84:85], s[14:15], 0, v[96:97]
	global_load_dwordx4 v[88:91], v[84:85], off offset:16
	global_load_dwordx4 v[180:183], v[84:85], off
	v_lshl_add_u64 v[84:85], s[18:19], 0, v[96:97]
	v_lshl_add_u64 v[98:99], s[20:21], 0, v[96:97]
	v_lshl_add_u64 v[192:193], s[16:17], 0, v[96:97]
	global_load_dwordx4 v[92:95], v[84:85], off offset:16
	global_load_dwordx4 v[184:187], v[84:85], off
	s_nop 0
	global_load_dwordx4 v[84:87], v[98:99], off offset:16
	global_load_dwordx4 v[188:191], v[98:99], off
	s_nop 0
	global_load_dwordx4 v[96:99], v[192:193], off offset:16
	s_nop 0
	global_load_dwordx4 v[192:195], v[192:193], off
	s_add_i32 s44, s44, s50
	s_and_b32 s27, s44, 31
	s_cmp_lg_u32 s27, 31
	v_cmp_eq_u32_e64 s[6:7], 15, v246
	s_cselect_b64 s[2:3], -1, 0
	s_and_b64 s[40:41], s[2:3], s[6:7]
	s_add_i32 s2, s44, 0x81
	s_mul_hi_i32 s39, s2, 0x5600
	s_mul_i32 s38, s2, 0x5600
	v_mov_b32_dpp v228, v144 row_shr:1 row_mask:0xf bank_mask:0xf bound_ctrl:1
	v_mov_b32_dpp v229, v145 row_shr:1 row_mask:0xf bank_mask:0xf bound_ctrl:1
	v_mov_b32_dpp v226, v146 row_shr:1 row_mask:0xf bank_mask:0xf bound_ctrl:1
	v_mov_b32_dpp v227, v147 row_shr:1 row_mask:0xf bank_mask:0xf bound_ctrl:1
	v_mov_b32_dpp v234, v132 row_shr:1 row_mask:0xf bank_mask:0xf bound_ctrl:1
	v_mov_b32_dpp v236, v133 row_shr:1 row_mask:0xf bank_mask:0xf bound_ctrl:1
	v_mov_b32_dpp v235, v134 row_shr:1 row_mask:0xf bank_mask:0xf bound_ctrl:1
	v_mov_b32_dpp v237, v135 row_shr:1 row_mask:0xf bank_mask:0xf bound_ctrl:1
	s_and_saveexec_b64 s[2:3], s[40:41]
	s_cbranch_execz .LBB0_759
	s_lshl_b64 s[4:5], s[38:39], 1
	s_waitcnt vmcnt(0)
	v_pk_mul_f32 v[200:201], v[146:147], v[174:175]
	v_pk_mul_f32 v[222:223], v[144:145], v[172:173]
	s_add_u32 s4, s56, s4
	v_pk_fma_f32 v[200:201], v[134:135], v[170:171], v[200:201]
	v_pk_fma_f32 v[222:223], v[132:133], v[168:169], v[222:223]
	s_addc_u32 s5, s57, s5
	v_cvt_pkrtz_f16_f32 v222, v222, v223
	v_cvt_pkrtz_f16_f32 v223, v200, v201
	v_lshl_add_u64 v[200:201], v[218:219], 1, s[4:5]
	flat_store_dwordx2 v[200:201], v[222:223]
	v_pk_mul_f32 v[222:223], v[146:147], v[170:171]
	v_pk_mul_f32 v[224:225], v[144:145], v[168:169]
	v_add_co_u32_e32 v200, vcc, 0x5000, v200
	v_cvt_pkrtz_f16_f32 v224, v224, v225
	v_cvt_pkrtz_f16_f32 v225, v222, v223
	v_addc_co_u32_e32 v201, vcc, 0, v201, vcc
	flat_store_dwordx2 v[200:201], v[224:225] offset:1536
.LBB0_759:
	s_or_b64 exec, exec, s[2:3]
	v_mov_b32_dpp v224, v136 row_shr:1 row_mask:0xf bank_mask:0xf bound_ctrl:1
	v_mov_b32_dpp v225, v137 row_shr:1 row_mask:0xf bank_mask:0xf bound_ctrl:1
	v_mov_b32_dpp v222, v138 row_shr:1 row_mask:0xf bank_mask:0xf bound_ctrl:1
	v_mov_b32_dpp v223, v139 row_shr:1 row_mask:0xf bank_mask:0xf bound_ctrl:1
	v_mov_b32_dpp v230, v140 row_shr:1 row_mask:0xf bank_mask:0xf bound_ctrl:1
	v_mov_b32_dpp v232, v141 row_shr:1 row_mask:0xf bank_mask:0xf bound_ctrl:1
	v_mov_b32_dpp v231, v142 row_shr:1 row_mask:0xf bank_mask:0xf bound_ctrl:1
	v_mov_b32_dpp v233, v143 row_shr:1 row_mask:0xf bank_mask:0xf bound_ctrl:1
	s_and_saveexec_b64 s[2:3], s[40:41]
	s_cbranch_execz .LBB0_761
	s_lshl_b64 s[4:5], s[38:39], 1
	s_waitcnt vmcnt(0)
	v_pk_mul_f32 v[200:201], v[138:139], v[186:187]
	v_pk_mul_f32 v[238:239], v[136:137], v[184:185]
	s_add_u32 s4, s56, s4
	v_pk_fma_f32 v[200:201], v[142:143], v[182:183], v[200:201]
	v_pk_fma_f32 v[238:239], v[140:141], v[180:181], v[238:239]
	s_addc_u32 s5, s57, s5
	v_cvt_pkrtz_f16_f32 v238, v238, v239
	v_cvt_pkrtz_f16_f32 v239, v200, v201
	v_lshl_add_u64 v[200:201], v[220:221], 1, s[4:5]
	flat_store_dwordx2 v[200:201], v[238:239]
	v_pk_mul_f32 v[238:239], v[138:139], v[182:183]
	v_pk_mul_f32 v[248:249], v[136:137], v[180:181]
	v_add_co_u32_e32 v200, vcc, 0x5000, v200
	v_cvt_pkrtz_f16_f32 v248, v248, v249
	v_cvt_pkrtz_f16_f32 v249, v238, v239
	v_addc_co_u32_e32 v201, vcc, 0, v201, vcc
	flat_store_dwordx2 v[200:201], v[248:249] offset:1536
.LBB0_761:
	s_or_b64 exec, exec, s[2:3]
	v_cmp_eq_u32_e64 s[2:3], 0, v246
	s_cmp_lg_u32 s27, 0
	s_cselect_b64 s[36:37], -1, 0
	v_mov_b32_e32 v201, v232
	v_mov_b32_e32 v200, v230
	s_waitcnt vmcnt(0)
	v_pk_fma_f32 v[200:201], v[180:181], v[200:201], v[192:193]
	v_mov_b32_e32 v232, v231
	v_pk_fma_f32 v[200:201], v[184:185], v[224:225], v[200:201]
	v_pk_fma_f32 v[230:231], v[182:183], v[232:233], v[194:195]
	v_pk_fma_f32 v[232:233], v[156:157], v[188:189], v[200:201]
	v_mov_b32_e32 v201, v236
	v_mov_b32_e32 v200, v234
	v_mov_b32_e32 v236, v235
	v_pk_fma_f32 v[234:235], v[170:171], v[236:237], v[178:179]
	v_pk_fma_f32 v[200:201], v[168:169], v[200:201], v[176:177]
	v_pk_fma_f32 v[230:231], v[186:187], v[222:223], v[230:231]
	v_pk_fma_f32 v[200:201], v[172:173], v[228:229], v[200:201]
	v_pk_fma_f32 v[234:235], v[174:175], v[226:227], v[234:235]
	v_pk_fma_f32 v[230:231], v[158:159], v[190:191], v[230:231]
	v_cmp_ne_u32_e64 s[4:5], 0, v246
	v_pk_fma_f32 v[234:235], v[162:163], v[166:167], v[234:235]
	v_pk_fma_f32 v[236:237], v[160:161], v[164:165], v[200:201]
	s_and_b64 s[36:37], s[2:3], s[36:37]
	s_mul_hi_i32 s27, s44, 0xac00
	s_mul_i32 s29, s44, 0xac00
	s_and_saveexec_b64 s[42:43], s[36:37]
	s_xor_b64 s[42:43], exec, s[42:43]
	s_cbranch_execz .LBB0_763
	s_add_u32 s64, s56, s29
	s_addc_u32 s65, s57, s27
	v_cvt_pkrtz_f16_f32 v200, v236, v237
	v_cvt_pkrtz_f16_f32 v201, v234, v235
	v_lshl_add_u64 v[234:235], v[218:219], 1, s[64:65]
	flat_store_dwordx2 v[234:235], v[200:201]
	v_cvt_pkrtz_f16_f32 v200, v232, v233
	v_cvt_pkrtz_f16_f32 v201, v230, v231
	v_lshl_add_u64 v[230:231], v[220:221], 1, s[64:65]
	flat_store_dwordx2 v[230:231], v[200:201]

; __device__ __forceinline__ u32x2 pack4(f32x4 v) { u32x2 r; r.x = cvt_pk_bf16(v[0], v[1]); r.y = cvt_pk_bf16(v[2], v[3]); return r; }
; __device__ __forceinline__ float sigmoidf_(float x) { return __builtin_amdgcn_rcpf(1.0f + __expf(-x)); }
;     __device__ __forceinline__ void operator()(AccRef acc, const pg8::Unit& u, int wr, int wc, int fr, int fq) const {
;     ...
;                     f32x4 s3 = dpp4<0x111>(h3), s2 = dpp4<0x111>(h2);
;                     if (fr == 0) { s3 = zero; s2 = zero; }
;                     const f32x4 c0 = bb[bj] + w0[bj] * s2 + w1[bj] * s3 + w2[bj] * h0;
;                     const f32x4 c1 = bb[bj] + w0[bj] * s3 + w1[bj] * h0 + w2[bj] * h1;
;                     const f32x4 c2 = bb[bj] + w0[bj] * h0 + w1[bj] * h1 + w2[bj] * h2;
;                     const f32x4 c3 = bb[bj] + w0[bj] * h1 + w1[bj] * h2 + w2[bj] * h3;
;                     if (bj == 0) { cv[0] = c0; cv[1] = c1; cv[2] = c2; cv[3] = c3; } else { cg[0] = c0; cg[1] = c1; cg[2] = c2; cg[3] = c3; }
;                     if (has_next && fr == 15) {
;                         const size_t o1 = ((size_t)(1 * NSLAB + slab + 1) * 2) * NUP;
;                         *(u32x2*)((bf16_t*)BND + o1 + fc) = pack4(w0[bj] * h2 + w1[bj] * h3); *(u32x2*)((bf16_t*)BND + o1 + NUP + fc) = pack4(w0[bj] * h3);
;                     }
;                 }
; #pragma unroll
;                 for (int m = 0; m < 4; ++m) {
;                     if (m < 2 && fr == 0 && !bstart) {
;                         const size_t o0 = ((size_t)(0 * NSLAB + slab) * 2 + m) * NUP;
;                         *(u32x2*)((bf16_t*)BND + o0 + fv) = pack4(cv[m]); *(u32x2*)((bf16_t*)BND + o0 + fg) = pack4(cg[m]);
;                     } else {
;                         f32x4 a;
; #pragma unroll
;                         for (int j = 0; j < 4; ++j) a[j] = cv[m][j] * cg[m][j] * sigmoidf_(cg[m][j]);
;                         *(u32x2*)(ACT + (size_t)(slab * 64 + 4 * fr + m) * DFF + fv) = pack4(a);
.LBB0_769:
	s_or_b64 exec, exec, s[42:43]
	v_pk_fma_f32 v[200:201], v[154:155], v[182:183], v[194:195]
	v_pk_fma_f32 v[222:223], v[152:153], v[180:181], v[192:193]
	v_pk_fma_f32 v[200:201], v[142:143], v[186:187], v[200:201]
	v_pk_fma_f32 v[222:223], v[140:141], v[184:185], v[222:223]
	v_pk_fma_f32 v[138:139], v[138:139], v[190:191], v[200:201]
	v_pk_fma_f32 v[200:201], v[136:137], v[188:189], v[222:223]
	v_pk_fma_f32 v[136:137], v[158:159], v[182:183], v[194:195]
	v_pk_fma_f32 v[156:157], v[156:157], v[180:181], v[192:193]
	v_pk_fma_f32 v[136:137], v[154:155], v[186:187], v[136:137]
	v_pk_fma_f32 v[152:153], v[152:153], v[184:185], v[156:157]
	v_pk_fma_f32 v[136:137], v[142:143], v[190:191], v[136:137]
	v_pk_fma_f32 v[142:143], v[150:151], v[170:171], v[178:179]
	v_pk_fma_f32 v[140:141], v[140:141], v[188:189], v[152:153]
	v_pk_fma_f32 v[142:143], v[134:135], v[174:175], v[142:143]
	v_pk_fma_f32 v[152:153], v[148:149], v[168:169], v[176:177]
	v_pk_fma_f32 v[142:143], v[146:147], v[166:167], v[142:143]
	v_pk_fma_f32 v[146:147], v[162:163], v[170:171], v[178:179]
	v_pk_fma_f32 v[152:153], v[132:133], v[172:173], v[152:153]
	v_pk_fma_f32 v[146:147], v[150:151], v[174:175], v[146:147]
	v_mul_f32_e32 v150, 0xbfb8aa3b, v140
	v_exp_f32_e32 v150, v150
	v_pk_fma_f32 v[134:135], v[134:135], v[166:167], v[146:147]
	v_mul_f32_e32 v147, 0xbfb8aa3b, v141
	v_exp_f32_e32 v147, v147
	v_add_f32_e32 v146, 1.0, v150
	v_pk_fma_f32 v[144:145], v[144:145], v[164:165], v[152:153]
	v_pk_fma_f32 v[152:153], v[160:161], v[168:169], v[176:177]
	v_rcp_f32_e32 v146, v146
	v_pk_fma_f32 v[148:149], v[148:149], v[172:173], v[152:153]
	v_mul_f32_e32 v134, v134, v136
	v_pk_fma_f32 v[132:133], v[132:133], v[164:165], v[148:149]
	v_mul_f32_e32 v144, v144, v200
	v_mul_f32_e32 v132, v132, v140
	v_mul_f32_e32 v133, v133, v141
	v_add_f32_e32 v140, 1.0, v147
	v_mul_f32_e32 v141, 0xbfb8aa3b, v136
	v_mul_f32_e32 v132, v132, v146
	v_rcp_f32_e32 v140, v140
	v_exp_f32_e32 v141, v141
	v_mul_f32_e32 v146, 0xbfb8aa3b, v137
	v_exp_f32_e32 v146, v146
	v_mul_f32_e32 v133, v133, v140
	v_add_f32_e32 v140, 1.0, v141
	v_rcp_f32_e32 v140, v140
	v_add_f32_e32 v141, 1.0, v146
	v_rcp_f32_e32 v141, v141
	v_mul_f32_e32 v136, v134, v140
	v_mul_f32_e32 v134, v135, v137
	v_mul_f32_e32 v135, v134, v141
	v_cvt_pkrtz_f16_f32 v135, v136, v135
	v_mul_f32_e32 v136, 0xbfb8aa3b, v200
	v_exp_f32_e32 v146, v136
	v_cvt_pkrtz_f16_f32 v134, v132, v133
	v_or_b32_e32 v132, 2, v246
	v_mov_b64_e32 v[140:141], s[22:23]
	v_mad_i64_i32 v[132:133], s[42:43], v132, s33, v[140:141]
	v_lshlrev_b64 v[136:137], 1, v[218:219]
	v_lshl_add_u64 v[132:133], v[132:133], 0, v[136:137]
	flat_store_dwordx2 v[132:133], v[134:135]
	v_add_f32_e32 v134, 1.0, v146
	v_mul_f32_e32 v135, 0xbfb8aa3b, v201
	v_rcp_f32_e32 v134, v134
	v_exp_f32_e32 v135, v135
	v_mul_f32_e32 v146, 0xbfb8aa3b, v139
	v_exp_f32_e32 v146, v146
	v_mul_f32_e32 v134, v144, v134
	v_mul_f32_e32 v144, v145, v201
	v_add_f32_e32 v135, 1.0, v135
	v_mul_f32_e32 v145, 0xbfb8aa3b, v138
	v_rcp_f32_e32 v135, v135
	v_exp_f32_e32 v145, v145
	v_mul_f32_e32 v138, v142, v138
	v_mul_f32_e32 v135, v144, v135
	v_add_f32_e32 v144, 1.0, v145
	v_rcp_f32_e32 v144, v144
	v_add_f32_e32 v145, 1.0, v146
	v_rcp_f32_e32 v145, v145
	v_mul_f32_e32 v142, v138, v144
	v_mul_f32_e32 v138, v143, v139
	v_mul_f32_e32 v139, v138, v145
	v_cvt_pkrtz_f16_f32 v138, v134, v135
	v_or_b32_e32 v134, 3, v246
	v_mad_i64_i32 v[134:135], s[42:43], v134, s33, v[140:141]
	v_cvt_pkrtz_f16_f32 v139, v142, v139
	v_lshl_add_u64 v[134:135], v[134:135], 0, v[136:137]
	flat_store_dwordx2 v[134:135], v[138:139]
	s_add_i32 s65, s44, 2
	s_and_b32 s63, s65, 31
	s_cmp_lg_u32 s63, 31
	s_cselect_b64 s[42:43], -1, 0
	s_and_b64 s[42:43], s[42:43], s[6:7]
	s_add_i32 s6, s44, 0x83
	s_mul_hi_i32 s7, s6, 0x5600
	s_mulk_i32 s6, 0x5600
	v_mov_b32_dpp v144, v112 row_shr:1 row_mask:0xf bank_mask:0xf bound_ctrl:1
	v_mov_b32_dpp v145, v113 row_shr:1 row_mask:0xf bank_mask:0xf bound_ctrl:1
	v_mov_b32_dpp v142, v114 row_shr:1 row_mask:0xf bank_mask:0xf bound_ctrl:1
	v_mov_b32_dpp v143, v115 row_shr:1 row_mask:0xf bank_mask:0xf bound_ctrl:1
	v_mov_b32_dpp v150, v100 row_shr:1 row_mask:0xf bank_mask:0xf bound_ctrl:1
	v_mov_b32_dpp v152, v101 row_shr:1 row_mask:0xf bank_mask:0xf bound_ctrl:1
	v_mov_b32_dpp v151, v102 row_shr:1 row_mask:0xf bank_mask:0xf bound_ctrl:1
	v_mov_b32_dpp v153, v103 row_shr:1 row_mask:0xf bank_mask:0xf bound_ctrl:1
	s_and_saveexec_b64 s[44:45], s[42:43]
	s_cbranch_execz .LBB0_771
	s_lshl_b64 s[66:67], s[6:7], 1
	v_pk_mul_f32 v[138:139], v[114:115], v[174:175]
	v_pk_mul_f32 v[140:141], v[112:113], v[172:173]
	s_add_u32 s66, s56, s66
	v_pk_fma_f32 v[138:139], v[102:103], v[170:171], v[138:139]
	v_pk_fma_f32 v[140:141], v[100:101], v[168:169], v[140:141]
	s_addc_u32 s67, s57, s67
	v_cvt_pkrtz_f16_f32 v140, v140, v141
	v_cvt_pkrtz_f16_f32 v141, v138, v139
	v_lshl_add_u64 v[138:139], v[218:219], 1, s[66:67]
	flat_store_dwordx2 v[138:139], v[140:141]
	v_pk_mul_f32 v[140:141], v[114:115], v[170:171]
	v_pk_mul_f32 v[146:147], v[112:113], v[168:169]
	v_add_co_u32_e32 v138, vcc, 0x5000, v138
	v_cvt_pkrtz_f16_f32 v146, v146, v147
	v_cvt_pkrtz_f16_f32 v147, v140, v141
	v_addc_co_u32_e32 v139, vcc, 0, v139, vcc
	flat_store_dwordx2 v[138:139], v[146:147] offset:1536
; __device__ __forceinline__ u32x2 pack4(f32x4 v) { u32x2 r; r.x = cvt_pk_bf16(v[0], v[1]); r.y = cvt_pk_bf16(v[2], v[3]); return r; }
;     __device__ __forceinline__ void operator()(AccRef acc, const pg8::Unit& u, int wr, int wc, int fr, int fq) const {
;     ...
;                     f32x4 s3 = dpp4<0x111>(h3), s2 = dpp4<0x111>(h2);
;                     if (fr == 0) { s3 = zero; s2 = zero; }
;                     const f32x4 c0 = bb[bj] + w0[bj] * s2 + w1[bj] * s3 + w2[bj] * h0;
;                     const f32x4 c1 = bb[bj] + w0[bj] * s3 + w1[bj] * h0 + w2[bj] * h1;
;                     const f32x4 c2 = bb[bj] + w0[bj] * h0 + w1[bj] * h1 + w2[bj] * h2;
;                     const f32x4 c3 = bb[bj] + w0[bj] * h1 + w1[bj] * h2 + w2[bj] * h3;
;                     if (bj == 0) { cv[0] = c0; cv[1] = c1; cv[2] = c2; cv[3] = c3; } else { cg[0] = c0; cg[1] = c1; cg[2] = c2; cg[3] = c3; }
;                     if (has_next && fr == 15) {
;                         const size_t o1 = ((size_t)(1 * NSLAB + slab + 1) * 2) * NUP;
;                         *(u32x2*)((bf16_t*)BND + o1 + fc) = pack4(w0[bj] * h2 + w1[bj] * h3); *(u32x2*)((bf16_t*)BND + o1 + NUP + fc) = pack4(w0[bj] * h3);
.LBB0_771:
	s_or_b64 exec, exec, s[44:45]
	v_mov_b32_dpp v140, v104 row_shr:1 row_mask:0xf bank_mask:0xf bound_ctrl:1
	v_mov_b32_dpp v141, v105 row_shr:1 row_mask:0xf bank_mask:0xf bound_ctrl:1
	v_mov_b32_dpp v138, v106 row_shr:1 row_mask:0xf bank_mask:0xf bound_ctrl:1
	v_mov_b32_dpp v139, v107 row_shr:1 row_mask:0xf bank_mask:0xf bound_ctrl:1
	v_mov_b32_dpp v146, v108 row_shr:1 row_mask:0xf bank_mask:0xf bound_ctrl:1
	v_mov_b32_dpp v148, v109 row_shr:1 row_mask:0xf bank_mask:0xf bound_ctrl:1
	v_mov_b32_dpp v147, v110 row_shr:1 row_mask:0xf bank_mask:0xf bound_ctrl:1
	v_mov_b32_dpp v149, v111 row_shr:1 row_mask:0xf bank_mask:0xf bound_ctrl:1
	s_and_saveexec_b64 s[44:45], s[42:43]
	s_cbranch_execz .LBB0_773
	s_lshl_b64 s[66:67], s[6:7], 1
	v_pk_mul_f32 v[154:155], v[106:107], v[186:187]
	v_pk_mul_f32 v[156:157], v[104:105], v[184:185]
	s_add_u32 s66, s56, s66
	v_pk_fma_f32 v[154:155], v[110:111], v[182:183], v[154:155]
	v_pk_fma_f32 v[156:157], v[108:109], v[180:181], v[156:157]
	s_addc_u32 s67, s57, s67
	v_cvt_pkrtz_f16_f32 v156, v156, v157
	v_cvt_pkrtz_f16_f32 v157, v154, v155
	v_lshl_add_u64 v[154:155], v[220:221], 1, s[66:67]
	flat_store_dwordx2 v[154:155], v[156:157]
	v_pk_mul_f32 v[156:157], v[106:107], v[182:183]
	v_pk_mul_f32 v[158:159], v[104:105], v[180:181]
	v_add_co_u32_e32 v154, vcc, 0x5000, v154
	v_cvt_pkrtz_f16_f32 v158, v158, v159
	v_cvt_pkrtz_f16_f32 v159, v156, v157
	v_addc_co_u32_e32 v155, vcc, 0, v155, vcc
	flat_store_dwordx2 v[154:155], v[158:159] offset:1536
.LBB0_773:
	s_or_b64 exec, exec, s[44:45]
	v_mov_b32_e32 v155, v148
	v_mov_b32_e32 v154, v146
	v_mov_b32_e32 v148, v147
	v_pk_fma_f32 v[146:147], v[182:183], v[148:149], v[194:195]
	v_pk_fma_f32 v[148:149], v[180:181], v[154:155], v[192:193]
	v_mov_b32_e32 v155, v152
	v_mov_b32_e32 v154, v150
	v_mov_b32_e32 v152, v151
	v_pk_fma_f32 v[150:151], v[170:171], v[152:153], v[178:179]
	v_pk_fma_f32 v[152:153], v[168:169], v[154:155], v[176:177]
	s_cmp_lg_u32 s63, 0
	v_pk_fma_f32 v[148:149], v[184:185], v[140:141], v[148:149]
	v_pk_fma_f32 v[146:147], v[186:187], v[138:139], v[146:147]
	v_pk_fma_f32 v[152:153], v[172:173], v[144:145], v[152:153]
	v_pk_fma_f32 v[150:151], v[174:175], v[142:143], v[150:151]
	s_cselect_b64 s[44:45], -1, 0
	s_xor_b64 s[4:5], s[4:5], -1
	v_pk_fma_f32 v[146:147], v[126:127], v[190:191], v[146:147]
	v_pk_fma_f32 v[148:149], v[124:125], v[188:189], v[148:149]
	v_pk_fma_f32 v[150:151], v[130:131], v[166:167], v[150:151]
	v_pk_fma_f32 v[152:153], v[128:129], v[164:165], v[152:153]
	s_and_b64 s[4:5], s[4:5], s[44:45]
	s_mul_hi_i32 s63, s65, 0xac00
	s_mul_i32 s64, s65, 0xac00
	s_and_saveexec_b64 s[44:45], s[4:5]
	s_xor_b64 s[44:45], exec, s[44:45]
	s_cbranch_execz .LBB0_775
	s_add_u32 s66, s56, s64
	s_addc_u32 s67, s57, s63
	v_cvt_pkrtz_f16_f32 v152, v152, v153
	v_cvt_pkrtz_f16_f32 v153, v150, v151
	v_lshl_add_u64 v[150:151], v[218:219], 1, s[66:67]
	v_cvt_pkrtz_f16_f32 v148, v148, v149
	v_cvt_pkrtz_f16_f32 v149, v146, v147
	v_lshl_add_u64 v[146:147], v[220:221], 1, s[66:67]
	flat_store_dwordx2 v[150:151], v[152:153]
	flat_store_dwordx2 v[146:147], v[148:149]

; __device__ __forceinline__ u32x2 pack4(f32x4 v) { u32x2 r; r.x = cvt_pk_bf16(v[0], v[1]); r.y = cvt_pk_bf16(v[2], v[3]); return r; }
; __device__ __forceinline__ float sigmoidf_(float x) { return __builtin_amdgcn_rcpf(1.0f + __expf(-x)); }
;     __device__ __forceinline__ void operator()(AccRef acc, const pg8::Unit& u, int wr, int wc, int fr, int fq) const {
;     ...
;                     f32x4 s3 = dpp4<0x111>(h3), s2 = dpp4<0x111>(h2);
;                     if (fr == 0) { s3 = zero; s2 = zero; }
;                     const f32x4 c0 = bb[bj] + w0[bj] * s2 + w1[bj] * s3 + w2[bj] * h0;
;                     const f32x4 c1 = bb[bj] + w0[bj] * s3 + w1[bj] * h0 + w2[bj] * h1;
;                     const f32x4 c2 = bb[bj] + w0[bj] * h0 + w1[bj] * h1 + w2[bj] * h2;
;                     const f32x4 c3 = bb[bj] + w0[bj] * h1 + w1[bj] * h2 + w2[bj] * h3;
;                     if (bj == 0) { cv[0] = c0; cv[1] = c1; cv[2] = c2; cv[3] = c3; } else { cg[0] = c0; cg[1] = c1; cg[2] = c2; cg[3] = c3; }
;                     if (has_next && fr == 15) {
;                         const size_t o1 = ((size_t)(1 * NSLAB + slab + 1) * 2) * NUP;
;                         *(u32x2*)((bf16_t*)BND + o1 + fc) = pack4(w0[bj] * h2 + w1[bj] * h3); *(u32x2*)((bf16_t*)BND + o1 + NUP + fc) = pack4(w0[bj] * h3);
;                     }
;                 }
; #pragma unroll
;                 for (int m = 0; m < 4; ++m) {
;                     if (m < 2 && fr == 0 && !bstart) {
;                         const size_t o0 = ((size_t)(0 * NSLAB + slab) * 2 + m) * NUP;
;                         *(u32x2*)((bf16_t*)BND + o0 + fv) = pack4(cv[m]); *(u32x2*)((bf16_t*)BND + o0 + fg) = pack4(cg[m]);
;                     } else {
;                         f32x4 a;
; #pragma unroll
;                         for (int j = 0; j < 4; ++j) a[j] = cv[m][j] * cg[m][j] * sigmoidf_(cg[m][j]);
;                         *(u32x2*)(ACT + (size_t)(slab * 64 + 4 * fr + m) * DFF + fv) = pack4(a);
.LBB0_781:
	s_or_b64 exec, exec, s[44:45]
	v_pk_fma_f32 v[138:139], v[118:119], v[182:183], v[194:195]
	v_pk_fma_f32 v[140:141], v[116:117], v[180:181], v[192:193]
	v_pk_fma_f32 v[138:139], v[110:111], v[186:187], v[138:139]
	v_pk_fma_f32 v[140:141], v[108:109], v[184:185], v[140:141]
	v_pk_fma_f32 v[106:107], v[106:107], v[190:191], v[138:139]
	v_pk_fma_f32 v[138:139], v[104:105], v[188:189], v[140:141]
	v_pk_fma_f32 v[104:105], v[126:127], v[182:183], v[194:195]
	v_pk_fma_f32 v[124:125], v[124:125], v[180:181], v[192:193]
	v_pk_fma_f32 v[104:105], v[118:119], v[186:187], v[104:105]
	v_pk_fma_f32 v[116:117], v[116:117], v[184:185], v[124:125]
	v_pk_fma_f32 v[110:111], v[110:111], v[190:191], v[104:105]
	v_pk_fma_f32 v[104:105], v[122:123], v[170:171], v[178:179]
	v_pk_fma_f32 v[108:109], v[108:109], v[188:189], v[116:117]
	v_pk_fma_f32 v[104:105], v[102:103], v[174:175], v[104:105]
	v_pk_fma_f32 v[116:117], v[120:121], v[168:169], v[176:177]
	v_pk_fma_f32 v[114:115], v[114:115], v[166:167], v[104:105]
	v_pk_fma_f32 v[104:105], v[130:131], v[170:171], v[178:179]
	v_pk_fma_f32 v[116:117], v[100:101], v[172:173], v[116:117]
	v_pk_fma_f32 v[104:105], v[122:123], v[174:175], v[104:105]
	v_pk_fma_f32 v[112:113], v[112:113], v[164:165], v[116:117]
	v_pk_fma_f32 v[102:103], v[102:103], v[166:167], v[104:105]
	v_mul_f32_e32 v104, 0xbfb8aa3b, v108
	v_exp_f32_e32 v118, v104
	v_pk_fma_f32 v[116:117], v[128:129], v[168:169], v[176:177]
	v_mul_f32_e32 v102, v102, v110
	v_pk_fma_f32 v[116:117], v[120:121], v[172:173], v[116:117]
	v_or_b32_e32 v104, 4, v218
	v_pk_fma_f32 v[100:101], v[100:101], v[164:165], v[116:117]
	v_mul_f32_e32 v117, 0xbfb8aa3b, v109
	v_add_f32_e32 v116, 1.0, v118
	v_exp_f32_e32 v117, v117
	v_rcp_f32_e32 v116, v116
	v_mul_f32_e32 v100, v100, v108
	v_mul_f32_e32 v101, v101, v109
	v_add_f32_e32 v108, 1.0, v117
	v_mul_f32_e32 v109, 0xbfb8aa3b, v110
	v_mul_f32_e32 v100, v100, v116
	v_rcp_f32_e32 v108, v108
	v_exp_f32_e32 v109, v109
	v_mul_f32_e32 v116, 0xbfb8aa3b, v111
	v_exp_f32_e32 v116, v116
	v_mul_f32_e32 v101, v101, v108
	v_add_f32_e32 v108, 1.0, v109
	v_rcp_f32_e32 v108, v108
	v_add_f32_e32 v109, 1.0, v116
	v_rcp_f32_e32 v109, v109
	v_ashrrev_i32_e32 v105, 31, v104
	v_mul_f32_e32 v108, v102, v108
	v_mul_f32_e32 v102, v103, v111
	v_mul_f32_e32 v103, v102, v109
	v_cvt_pkrtz_f16_f32 v102, v100, v101
	v_cvt_pkrtz_f16_f32 v103, v108, v103
	v_or_b32_e32 v100, 2, v154
	v_mov_b64_e32 v[108:109], s[22:23]
	v_mul_f32_e32 v101, 0xbfb8aa3b, v138
	v_exp_f32_e32 v110, v101
	v_mad_i64_i32 v[100:101], s[44:45], v100, s33, v[108:109]
	v_lshl_add_u64 v[100:101], v[100:101], 0, v[136:137]
	flat_store_dwordx2 v[100:101], v[102:103]
	v_mul_f32_e32 v103, 0xbfb8aa3b, v139
	v_exp_f32_e32 v103, v103
	v_add_f32_e32 v102, 1.0, v110
	v_rcp_f32_e32 v102, v102
	v_mul_f32_e32 v111, 0xbfb8aa3b, v106
	v_add_f32_e32 v103, 1.0, v103
	v_mul_f32_e32 v110, v112, v138
	v_rcp_f32_e32 v103, v103
	v_exp_f32_e32 v111, v111
	v_mul_f32_e32 v112, 0xbfb8aa3b, v107
	v_exp_f32_e32 v112, v112
	v_mul_f32_e32 v102, v110, v102
	v_mul_f32_e32 v110, v113, v139
	v_mul_f32_e32 v103, v110, v103
	v_add_f32_e32 v110, 1.0, v111
	v_rcp_f32_e32 v110, v110
	v_add_f32_e32 v111, 1.0, v112
	v_rcp_f32_e32 v111, v111
	v_mul_f32_e32 v106, v114, v106
	v_mul_f32_e32 v110, v106, v110
	v_mul_f32_e32 v106, v115, v107
	v_mul_f32_e32 v107, v106, v111
	v_cvt_pkrtz_f16_f32 v106, v102, v103
	v_or_b32_e32 v102, 3, v154
	v_mad_i64_i32 v[102:103], s[44:45], v102, s33, v[108:109]
	v_cvt_pkrtz_f16_f32 v107, v110, v107
	v_lshl_add_u64 v[102:103], v[102:103], 0, v[136:137]
	flat_store_dwordx2 v[102:103], v[106:107]
	v_mov_b32_dpp v114, v44 row_shr:1 row_mask:0xf bank_mask:0xf bound_ctrl:1
	v_mov_b32_dpp v115, v45 row_shr:1 row_mask:0xf bank_mask:0xf bound_ctrl:1
	v_mov_b32_dpp v112, v46 row_shr:1 row_mask:0xf bank_mask:0xf bound_ctrl:1
	v_mov_b32_dpp v113, v47 row_shr:1 row_mask:0xf bank_mask:0xf bound_ctrl:1
	v_mov_b32_dpp v120, v36 row_shr:1 row_mask:0xf bank_mask:0xf bound_ctrl:1
	v_mov_b32_dpp v122, v37 row_shr:1 row_mask:0xf bank_mask:0xf bound_ctrl:1
	v_mov_b32_dpp v121, v38 row_shr:1 row_mask:0xf bank_mask:0xf bound_ctrl:1
	v_mov_b32_dpp v123, v39 row_shr:1 row_mask:0xf bank_mask:0xf bound_ctrl:1
	s_and_saveexec_b64 s[44:45], s[40:41]
	s_cbranch_execz .LBB0_783
	s_lshl_b64 s[66:67], s[38:39], 1
	v_pk_mul_f32 v[106:107], v[46:47], v[70:71]
	v_pk_mul_f32 v[108:109], v[44:45], v[68:69]
	s_add_u32 s66, s56, s66
	v_pk_fma_f32 v[106:107], v[38:39], v[78:79], v[106:107]
	v_pk_fma_f32 v[108:109], v[36:37], v[76:77], v[108:109]
	s_addc_u32 s67, s57, s67
	v_cvt_pkrtz_f16_f32 v108, v108, v109
	v_cvt_pkrtz_f16_f32 v109, v106, v107
	v_lshl_add_u64 v[106:107], v[218:219], 1, s[66:67]
	flat_store_dwordx2 v[106:107], v[108:109] offset:8
	v_pk_mul_f32 v[106:107], v[46:47], v[78:79]
	v_pk_mul_f32 v[108:109], v[44:45], v[76:77]
	s_nop 0
	v_cvt_pkrtz_f16_f32 v108, v108, v109
	v_cvt_pkrtz_f16_f32 v109, v106, v107
	v_lshl_add_u64 v[106:107], v[104:105], 1, s[66:67]
	v_add_co_u32_e32 v106, vcc, 0x5000, v106
	s_nop 1
	v_addc_co_u32_e32 v107, vcc, 0, v107, vcc
	flat_store_dwordx2 v[106:107], v[108:109] offset:1536
; __device__ __forceinline__ u32x2 pack4(f32x4 v) { u32x2 r; r.x = cvt_pk_bf16(v[0], v[1]); r.y = cvt_pk_bf16(v[2], v[3]); return r; }
;     __device__ __forceinline__ void operator()(AccRef acc, const pg8::Unit& u, int wr, int wc, int fr, int fq) const {
;     ...
;                     f32x4 s3 = dpp4<0x111>(h3), s2 = dpp4<0x111>(h2);
;                     if (fr == 0) { s3 = zero; s2 = zero; }
;                     const f32x4 c0 = bb[bj] + w0[bj] * s2 + w1[bj] * s3 + w2[bj] * h0;
;                     const f32x4 c1 = bb[bj] + w0[bj] * s3 + w1[bj] * h0 + w2[bj] * h1;
;                     const f32x4 c2 = bb[bj] + w0[bj] * h0 + w1[bj] * h1 + w2[bj] * h2;
;                     const f32x4 c3 = bb[bj] + w0[bj] * h1 + w1[bj] * h2 + w2[bj] * h3;
;                     if (bj == 0) { cv[0] = c0; cv[1] = c1; cv[2] = c2; cv[3] = c3; } else { cg[0] = c0; cg[1] = c1; cg[2] = c2; cg[3] = c3; }
;                     if (has_next && fr == 15) {
;                         const size_t o1 = ((size_t)(1 * NSLAB + slab + 1) * 2) * NUP;
;                         *(u32x2*)((bf16_t*)BND + o1 + fc) = pack4(w0[bj] * h2 + w1[bj] * h3); *(u32x2*)((bf16_t*)BND + o1 + NUP + fc) = pack4(w0[bj] * h3);
;                     }
;                 }
; #pragma unroll
;                 for (int m = 0; m < 4; ++m) {
;                     if (m < 2 && fr == 0 && !bstart) {
;                         const size_t o0 = ((size_t)(0 * NSLAB + slab) * 2 + m) * NUP;
;                         *(u32x2*)((bf16_t*)BND + o0 + fv) = pack4(cv[m]); *(u32x2*)((bf16_t*)BND + o0 + fg) = pack4(cg[m]);
.LBB0_783:
	s_or_b64 exec, exec, s[44:45]
	v_add_u32_e32 v106, 0x1584, v218
	v_ashrrev_i32_e32 v107, 31, v106
	v_mov_b32_dpp v110, v52 row_shr:1 row_mask:0xf bank_mask:0xf bound_ctrl:1
	v_mov_b32_dpp v111, v53 row_shr:1 row_mask:0xf bank_mask:0xf bound_ctrl:1
	v_mov_b32_dpp v108, v54 row_shr:1 row_mask:0xf bank_mask:0xf bound_ctrl:1
	v_mov_b32_dpp v109, v55 row_shr:1 row_mask:0xf bank_mask:0xf bound_ctrl:1
	v_mov_b32_dpp v116, v40 row_shr:1 row_mask:0xf bank_mask:0xf bound_ctrl:1
	v_mov_b32_dpp v118, v41 row_shr:1 row_mask:0xf bank_mask:0xf bound_ctrl:1
	v_mov_b32_dpp v117, v42 row_shr:1 row_mask:0xf bank_mask:0xf bound_ctrl:1
	v_mov_b32_dpp v119, v43 row_shr:1 row_mask:0xf bank_mask:0xf bound_ctrl:1
	s_and_saveexec_b64 s[44:45], s[40:41]
	s_cbranch_execz .LBB0_785
	s_lshl_b64 s[38:39], s[38:39], 1
	v_pk_mul_f32 v[124:125], v[54:55], v[94:95]
	v_pk_mul_f32 v[126:127], v[52:53], v[92:93]
	s_add_u32 s38, s56, s38
	v_pk_fma_f32 v[124:125], v[42:43], v[90:91], v[124:125]
	v_pk_fma_f32 v[126:127], v[40:41], v[88:89], v[126:127]
	s_addc_u32 s39, s57, s39
	v_cvt_pkrtz_f16_f32 v126, v126, v127
	v_cvt_pkrtz_f16_f32 v127, v124, v125
	v_lshl_add_u64 v[124:125], v[106:107], 1, s[38:39]
	flat_store_dwordx2 v[124:125], v[126:127]
	v_pk_mul_f32 v[126:127], v[54:55], v[90:91]
	v_pk_mul_f32 v[128:129], v[52:53], v[88:89]
	v_add_co_u32_e32 v124, vcc, 0x5000, v124
	v_cvt_pkrtz_f16_f32 v128, v128, v129
	v_cvt_pkrtz_f16_f32 v129, v126, v127
	v_addc_co_u32_e32 v125, vcc, 0, v125, vcc
	flat_store_dwordx2 v[124:125], v[128:129] offset:1536
.LBB0_785:
	s_or_b64 exec, exec, s[44:45]
	v_mov_b32_e32 v125, v118
	v_mov_b32_e32 v124, v116
	v_mov_b32_e32 v118, v117
	v_pk_fma_f32 v[116:117], v[90:91], v[118:119], v[98:99]
	v_pk_fma_f32 v[118:119], v[88:89], v[124:125], v[96:97]
	v_mov_b32_e32 v125, v122
	v_mov_b32_e32 v124, v120
	v_mov_b32_e32 v122, v121
	v_pk_fma_f32 v[120:121], v[78:79], v[122:123], v[82:83]
	v_pk_fma_f32 v[122:123], v[76:77], v[124:125], v[80:81]
	v_pk_fma_f32 v[118:119], v[92:93], v[110:111], v[118:119]
	v_pk_fma_f32 v[116:117], v[94:95], v[108:109], v[116:117]
	v_pk_fma_f32 v[122:123], v[68:69], v[114:115], v[122:123]
	v_pk_fma_f32 v[120:121], v[70:71], v[112:113], v[120:121]
	v_pk_fma_f32 v[116:117], v[62:63], v[86:87], v[116:117]
	v_pk_fma_f32 v[118:119], v[60:61], v[84:85], v[118:119]
	v_pk_fma_f32 v[120:121], v[66:67], v[74:75], v[120:121]
	v_pk_fma_f32 v[122:123], v[64:65], v[72:73], v[122:123]
	s_and_saveexec_b64 s[38:39], s[36:37]
	s_xor_b64 s[38:39], exec, s[38:39]
	s_cbranch_execz .LBB0_787
	s_add_u32 s40, s56, s29
	s_addc_u32 s41, s57, s27
	v_cvt_pkrtz_f16_f32 v122, v122, v123
	v_cvt_pkrtz_f16_f32 v123, v120, v121
	v_lshl_add_u64 v[120:121], v[218:219], 1, s[40:41]
	v_cvt_pkrtz_f16_f32 v118, v118, v119
	v_cvt_pkrtz_f16_f32 v119, v116, v117
	v_lshl_add_u64 v[116:117], v[106:107], 1, s[40:41]
	flat_store_dwordx2 v[120:121], v[122:123] offset:8
	flat_store_dwordx2 v[116:117], v[118:119]

; __device__ __forceinline__ u32x2 pack4(f32x4 v) { u32x2 r; r.x = cvt_pk_bf16(v[0], v[1]); r.y = cvt_pk_bf16(v[2], v[3]); return r; }
; __device__ __forceinline__ float sigmoidf_(float x) { return __builtin_amdgcn_rcpf(1.0f + __expf(-x)); }
;     __device__ __forceinline__ void operator()(AccRef acc, const pg8::Unit& u, int wr, int wc, int fr, int fq) const {
;     ...
;                     f32x4 s3 = dpp4<0x111>(h3), s2 = dpp4<0x111>(h2);
;                     if (fr == 0) { s3 = zero; s2 = zero; }
;                     const f32x4 c0 = bb[bj] + w0[bj] * s2 + w1[bj] * s3 + w2[bj] * h0;
;                     const f32x4 c1 = bb[bj] + w0[bj] * s3 + w1[bj] * h0 + w2[bj] * h1;
;                     const f32x4 c2 = bb[bj] + w0[bj] * h0 + w1[bj] * h1 + w2[bj] * h2;
;                     const f32x4 c3 = bb[bj] + w0[bj] * h1 + w1[bj] * h2 + w2[bj] * h3;
;                     if (bj == 0) { cv[0] = c0; cv[1] = c1; cv[2] = c2; cv[3] = c3; } else { cg[0] = c0; cg[1] = c1; cg[2] = c2; cg[3] = c3; }
;                     if (has_next && fr == 15) {
;                         const size_t o1 = ((size_t)(1 * NSLAB + slab + 1) * 2) * NUP;
;                         *(u32x2*)((bf16_t*)BND + o1 + fc) = pack4(w0[bj] * h2 + w1[bj] * h3); *(u32x2*)((bf16_t*)BND + o1 + NUP + fc) = pack4(w0[bj] * h3);
;                     }
;                 }
; #pragma unroll
;                 for (int m = 0; m < 4; ++m) {
;                     if (m < 2 && fr == 0 && !bstart) {
;                         const size_t o0 = ((size_t)(0 * NSLAB + slab) * 2 + m) * NUP;
;                         *(u32x2*)((bf16_t*)BND + o0 + fv) = pack4(cv[m]); *(u32x2*)((bf16_t*)BND + o0 + fg) = pack4(cg[m]);
;                     } else {
;                         f32x4 a;
; #pragma unroll
;                         for (int j = 0; j < 4; ++j) a[j] = cv[m][j] * cg[m][j] * sigmoidf_(cg[m][j]);
;                         *(u32x2*)(ACT + (size_t)(slab * 64 + 4 * fr + m) * DFF + fv) = pack4(a);
.LBB0_793:
	s_or_b64 exec, exec, s[36:37]
	v_pk_fma_f32 v[60:61], v[60:61], v[88:89], v[96:97]
	v_pk_fma_f32 v[110:111], v[56:57], v[88:89], v[96:97]
	v_pk_fma_f32 v[56:57], v[56:57], v[92:93], v[60:61]
	v_pk_fma_f32 v[110:111], v[40:41], v[92:93], v[110:111]
	v_pk_fma_f32 v[40:41], v[40:41], v[84:85], v[56:57]
	v_pk_fma_f32 v[56:57], v[50:51], v[78:79], v[82:83]
	v_pk_fma_f32 v[62:63], v[62:63], v[90:91], v[98:99]
	v_pk_fma_f32 v[56:57], v[38:39], v[70:71], v[56:57]
	v_pk_fma_f32 v[108:109], v[58:59], v[90:91], v[98:99]
	v_pk_fma_f32 v[46:47], v[46:47], v[74:75], v[56:57]
	v_pk_fma_f32 v[56:57], v[66:67], v[78:79], v[82:83]
	v_pk_fma_f32 v[58:59], v[58:59], v[94:95], v[62:63]
	v_pk_fma_f32 v[50:51], v[50:51], v[70:71], v[56:57]
	v_mul_f32_e32 v56, 0xbfb8aa3b, v40
	v_pk_fma_f32 v[108:109], v[42:43], v[94:95], v[108:109]
	v_pk_fma_f32 v[42:43], v[42:43], v[86:87], v[58:59]
	v_pk_fma_f32 v[58:59], v[48:49], v[76:77], v[80:81]
	v_exp_f32_e32 v56, v56
	v_pk_fma_f32 v[58:59], v[36:37], v[68:69], v[58:59]
	v_pk_fma_f32 v[38:39], v[38:39], v[74:75], v[50:51]
	v_pk_fma_f32 v[44:45], v[44:45], v[72:73], v[58:59]
	v_pk_fma_f32 v[58:59], v[64:65], v[76:77], v[80:81]
	v_mul_f32_e32 v38, v38, v42
	v_pk_fma_f32 v[48:49], v[48:49], v[68:69], v[58:59]
	v_mul_f32_e32 v39, v39, v43
	v_pk_fma_f32 v[36:37], v[36:37], v[72:73], v[48:49]
	v_add_f32_e32 v48, 1.0, v56
	v_mul_f32_e32 v49, 0xbfb8aa3b, v41
	v_rcp_f32_e32 v48, v48
	v_exp_f32_e32 v49, v49
	v_mul_f32_e32 v36, v36, v40
	v_mul_f32_e32 v37, v37, v41
	v_mul_f32_e32 v36, v36, v48
	v_add_f32_e32 v40, 1.0, v49
	v_mul_f32_e32 v41, 0xbfb8aa3b, v42
	v_mul_f32_e32 v48, 0xbfb8aa3b, v43
	v_rcp_f32_e32 v40, v40
	v_exp_f32_e32 v41, v41
	v_exp_f32_e32 v48, v48
	v_pk_fma_f32 v[52:53], v[52:53], v[84:85], v[110:111]
	v_mul_f32_e32 v37, v37, v40
	v_add_f32_e32 v40, 1.0, v41
	v_add_f32_e32 v41, 1.0, v48
	v_rcp_f32_e32 v40, v40
	v_rcp_f32_e32 v41, v41
	v_cvt_pkrtz_f16_f32 v36, v36, v37
	v_pk_fma_f32 v[54:55], v[54:55], v[86:87], v[108:109]
	v_mul_f32_e32 v38, v38, v40
	v_mul_f32_e32 v39, v39, v41
	v_mul_f32_e32 v40, 0xbfb8aa3b, v52
	v_cvt_pkrtz_f16_f32 v37, v38, v39
	v_exp_f32_e32 v40, v40
	flat_store_dwordx2 v[132:133], v[36:37] offset:8
	v_mul_f32_e32 v37, 0xbfb8aa3b, v53
	v_exp_f32_e32 v37, v37
	v_add_f32_e32 v36, 1.0, v40
	v_rcp_f32_e32 v36, v36
	v_mul_f32_e32 v39, 0xbfb8aa3b, v54
	v_add_f32_e32 v37, 1.0, v37
	v_rcp_f32_e32 v37, v37
	v_exp_f32_e32 v39, v39
	v_mul_f32_e32 v40, 0xbfb8aa3b, v55
	v_exp_f32_e32 v40, v40
	v_mul_f32_e32 v38, v44, v52
	v_mul_f32_e32 v36, v38, v36
	v_mul_f32_e32 v38, v45, v53
	v_mul_f32_e32 v37, v38, v37
	v_add_f32_e32 v38, 1.0, v39
	v_rcp_f32_e32 v38, v38
	v_add_f32_e32 v39, 1.0, v40
	v_rcp_f32_e32 v39, v39
	v_mul_f32_e32 v40, v46, v54
	v_mul_f32_e32 v38, v40, v38
	v_mul_f32_e32 v40, v47, v55
	v_mul_f32_e32 v39, v40, v39
	v_cvt_pkrtz_f16_f32 v36, v36, v37
	v_cvt_pkrtz_f16_f32 v37, v38, v39
	flat_store_dwordx2 v[134:135], v[36:37] offset:8
	v_mov_b32_dpp v42, v4 row_shr:1 row_mask:0xf bank_mask:0xf bound_ctrl:1
	v_mov_b32_dpp v43, v5 row_shr:1 row_mask:0xf bank_mask:0xf bound_ctrl:1
	v_mov_b32_dpp v40, v6 row_shr:1 row_mask:0xf bank_mask:0xf bound_ctrl:1
	v_mov_b32_dpp v41, v7 row_shr:1 row_mask:0xf bank_mask:0xf bound_ctrl:1
	v_mov_b32_dpp v48, v8 row_shr:1 row_mask:0xf bank_mask:0xf bound_ctrl:1
	v_mov_b32_dpp v50, v9 row_shr:1 row_mask:0xf bank_mask:0xf bound_ctrl:1
	v_mov_b32_dpp v49, v10 row_shr:1 row_mask:0xf bank_mask:0xf bound_ctrl:1
	v_mov_b32_dpp v51, v11 row_shr:1 row_mask:0xf bank_mask:0xf bound_ctrl:1
	s_and_saveexec_b64 s[36:37], s[42:43]
	s_cbranch_execz .LBB0_795
	s_lshl_b64 s[38:39], s[6:7], 1
	v_pk_mul_f32 v[36:37], v[6:7], v[70:71]
	v_pk_mul_f32 v[38:39], v[4:5], v[68:69]
	s_add_u32 s38, s56, s38
	v_pk_fma_f32 v[36:37], v[10:11], v[78:79], v[36:37]
	v_pk_fma_f32 v[38:39], v[8:9], v[76:77], v[38:39]
	s_addc_u32 s39, s57, s39
	v_cvt_pkrtz_f16_f32 v38, v38, v39
	v_cvt_pkrtz_f16_f32 v39, v36, v37
	v_lshl_add_u64 v[36:37], v[218:219], 1, s[38:39]
	flat_store_dwordx2 v[36:37], v[38:39] offset:8
	v_pk_mul_f32 v[36:37], v[6:7], v[78:79]
	v_pk_mul_f32 v[38:39], v[4:5], v[76:77]
	s_nop 0
	v_cvt_pkrtz_f16_f32 v38, v38, v39
	v_cvt_pkrtz_f16_f32 v39, v36, v37
	v_lshl_add_u64 v[36:37], v[104:105], 1, s[38:39]
	v_add_co_u32_e32 v36, vcc, 0x5000, v36
	s_nop 1
	v_addc_co_u32_e32 v37, vcc, 0, v37, vcc
	flat_store_dwordx2 v[36:37], v[38:39] offset:1536
; __device__ __forceinline__ u32x2 pack4(f32x4 v) { u32x2 r; r.x = cvt_pk_bf16(v[0], v[1]); r.y = cvt_pk_bf16(v[2], v[3]); return r; }
;     __device__ __forceinline__ void operator()(AccRef acc, const pg8::Unit& u, int wr, int wc, int fr, int fq) const {
;     ...
;                     f32x4 s3 = dpp4<0x111>(h3), s2 = dpp4<0x111>(h2);
;                     if (fr == 0) { s3 = zero; s2 = zero; }
;                     const f32x4 c0 = bb[bj] + w0[bj] * s2 + w1[bj] * s3 + w2[bj] * h0;
;                     const f32x4 c1 = bb[bj] + w0[bj] * s3 + w1[bj] * h0 + w2[bj] * h1;
;                     const f32x4 c2 = bb[bj] + w0[bj] * h0 + w1[bj] * h1 + w2[bj] * h2;
;                     const f32x4 c3 = bb[bj] + w0[bj] * h1 + w1[bj] * h2 + w2[bj] * h3;
;                     if (bj == 0) { cv[0] = c0; cv[1] = c1; cv[2] = c2; cv[3] = c3; } else { cg[0] = c0; cg[1] = c1; cg[2] = c2; cg[3] = c3; }
;                     if (has_next && fr == 15) {
;                         const size_t o1 = ((size_t)(1 * NSLAB + slab + 1) * 2) * NUP;
;                         *(u32x2*)((bf16_t*)BND + o1 + fc) = pack4(w0[bj] * h2 + w1[bj] * h3); *(u32x2*)((bf16_t*)BND + o1 + NUP + fc) = pack4(w0[bj] * h3);
;                     }
;                 }
; #pragma unroll
;                 for (int m = 0; m < 4; ++m) {
;                     if (m < 2 && fr == 0 && !bstart) {
;                         const size_t o0 = ((size_t)(0 * NSLAB + slab) * 2 + m) * NUP;
;                         *(u32x2*)((bf16_t*)BND + o0 + fv) = pack4(cv[m]); *(u32x2*)((bf16_t*)BND + o0 + fg) = pack4(cg[m]);
.LBB0_795:
	s_or_b64 exec, exec, s[36:37]
	v_mov_b32_dpp v38, v12 row_shr:1 row_mask:0xf bank_mask:0xf bound_ctrl:1
	v_mov_b32_dpp v39, v13 row_shr:1 row_mask:0xf bank_mask:0xf bound_ctrl:1
	v_mov_b32_dpp v36, v14 row_shr:1 row_mask:0xf bank_mask:0xf bound_ctrl:1
	v_mov_b32_dpp v37, v15 row_shr:1 row_mask:0xf bank_mask:0xf bound_ctrl:1
	v_mov_b32_dpp v44, v16 row_shr:1 row_mask:0xf bank_mask:0xf bound_ctrl:1
	v_mov_b32_dpp v46, v17 row_shr:1 row_mask:0xf bank_mask:0xf bound_ctrl:1
	v_mov_b32_dpp v45, v18 row_shr:1 row_mask:0xf bank_mask:0xf bound_ctrl:1
	v_mov_b32_dpp v47, v19 row_shr:1 row_mask:0xf bank_mask:0xf bound_ctrl:1
	s_and_saveexec_b64 s[36:37], s[42:43]
	s_cbranch_execz .LBB0_797
	s_lshl_b64 s[6:7], s[6:7], 1
	v_pk_mul_f32 v[52:53], v[14:15], v[94:95]
	v_pk_mul_f32 v[54:55], v[12:13], v[92:93]
	s_add_u32 s6, s56, s6
	v_pk_fma_f32 v[52:53], v[18:19], v[90:91], v[52:53]
	v_pk_fma_f32 v[54:55], v[16:17], v[88:89], v[54:55]
	s_addc_u32 s7, s57, s7
	v_cvt_pkrtz_f16_f32 v54, v54, v55
	v_cvt_pkrtz_f16_f32 v55, v52, v53
	v_lshl_add_u64 v[52:53], v[106:107], 1, s[6:7]
	flat_store_dwordx2 v[52:53], v[54:55]
	v_pk_mul_f32 v[54:55], v[14:15], v[90:91]
	v_pk_mul_f32 v[56:57], v[12:13], v[88:89]
	v_add_co_u32_e32 v52, vcc, 0x5000, v52
	v_cvt_pkrtz_f16_f32 v56, v56, v57
	v_cvt_pkrtz_f16_f32 v57, v54, v55
	v_addc_co_u32_e32 v53, vcc, 0, v53, vcc
	flat_store_dwordx2 v[52:53], v[56:57] offset:1536
.LBB0_797:
	s_or_b64 exec, exec, s[36:37]
	v_mov_b32_e32 v53, v46
	v_mov_b32_e32 v52, v44
	v_mov_b32_e32 v46, v45
	v_pk_fma_f32 v[44:45], v[90:91], v[46:47], v[98:99]
	v_pk_fma_f32 v[46:47], v[88:89], v[52:53], v[96:97]
	v_mov_b32_e32 v53, v50
	v_mov_b32_e32 v52, v48
	v_mov_b32_e32 v50, v49
	v_pk_fma_f32 v[48:49], v[78:79], v[50:51], v[82:83]
	v_pk_fma_f32 v[50:51], v[76:77], v[52:53], v[80:81]
	v_pk_fma_f32 v[46:47], v[92:93], v[38:39], v[46:47]
	v_pk_fma_f32 v[44:45], v[94:95], v[36:37], v[44:45]
	v_pk_fma_f32 v[50:51], v[68:69], v[42:43], v[50:51]
	v_pk_fma_f32 v[48:49], v[70:71], v[40:41], v[48:49]
	v_pk_fma_f32 v[44:45], v[30:31], v[86:87], v[44:45]
	v_pk_fma_f32 v[46:47], v[28:29], v[84:85], v[46:47]
	v_pk_fma_f32 v[48:49], v[34:35], v[74:75], v[48:49]
	v_pk_fma_f32 v[50:51], v[32:33], v[72:73], v[50:51]
	s_and_saveexec_b64 s[2:3], s[4:5]
	s_xor_b64 s[2:3], exec, s[2:3]
	s_cbranch_execz .LBB0_799
	s_add_u32 s6, s56, s64
	s_addc_u32 s7, s57, s63
	v_cvt_pkrtz_f16_f32 v50, v50, v51
	v_cvt_pkrtz_f16_f32 v51, v48, v49
	v_lshl_add_u64 v[48:49], v[218:219], 1, s[6:7]
	v_cvt_pkrtz_f16_f32 v46, v46, v47
	v_cvt_pkrtz_f16_f32 v47, v44, v45
	v_lshl_add_u64 v[44:45], v[106:107], 1, s[6:7]
	flat_store_dwordx2 v[48:49], v[50:51] offset:8
	flat_store_dwordx2 v[44:45], v[46:47]
